# K-loop LDS-DMA rebalanced 4+4 per load phase (SA(*,0) pieces issued one phase later, counted vmcnt 8/6) combined with static setprio, on top of v72
# speedup vs baseline: 1.0046x; 1.0046x over previous
; #define PG8_STAGE(bufoff, gbase, voff) do { _Pragma("unroll") for (int _i = 0; _i < 2; ++_i) \
;         __builtin_amdgcn_global_load_lds((const unsigned*)((const char*)(gbase) + (voff)[_i]), (PG8_LAS unsigned*)(lds + (bufoff) + ldsw + _i * 8192), 16, 0, 0); } while (0)
; #define PG8_LDA(dst, b, h) do { _Pragma("unroll") for (int m = 0; m < 4; ++m) _Pragma("unroll") for (int k = 0; k < 2; ++k) dst[m][k] = *(const PG8_LAS bf16x8*)(lds + PG8_SA(b, h) + aoff + m * 2048 + k * 1024); } while (0)
; #define PG8_LDB(dst, b, h) do { _Pragma("unroll") for (int n = 0; n < 2; ++n) _Pragma("unroll") for (int k = 0; k < 2; ++k) dst[n][k] = *(const PG8_LAS bf16x8*)(lds + PG8_SB(b, h) + boff + n * 2048 + k * 1024); } while (0)
; #define PG8_MMA(ai, bj, At, Bt) do { __builtin_amdgcn_s_setprio(1); _Pragma("unroll") for (int m = 0; m < 4; ++m) _Pragma("unroll") for (int n = 0; n < 2; ++n) _Pragma("unroll") for (int k = 0; k < 2; ++k) \
;         acc[ai][bj][m][n] = __builtin_amdgcn_mfma_f32_16x16x32_bf16(Bt[n][k], At[m][k], acc[ai][bj][m][n], 0, 0, 0); __builtin_amdgcn_s_setprio(0); } while (0)
; #define PG8_WAIT_V(n) asm volatile("s_waitcnt vmcnt(" #n ")" ::: "memory")
; #define PG8_WAIT_L(n) asm volatile("s_waitcnt lgkmcnt(" #n ")" ::: "memory")
; #define PG8_BAR __builtin_amdgcn_s_barrier()
; #define PG8_SCHED __builtin_amdgcn_sched_barrier(0)
; template <class Epi, class Sched, bool ALIGN_EPI = false, bool SP2 = false>
; __device__ __forceinline__ void gemm_phase(PG8_LAS unsigned char* lds, const Gemm g, const Sched& S, const Epi& E, const int tid_in) {
;     ...
;             PG8_LDB(B0, 0, 0); PG8_LDB(B1, 0, 1); PG8_SCHED; PG8_LDA(At, 0, 0); PG8_STAGE(PG8_SA(1, 1), a1 + hstep, voffA);
;             PG8_WAIT_V(8); PG8_WAIT_L(0); PG8_BAR; PG8_MMA(0, 0, At, B0); PG8_MMA(0, 1, At, B1); PG8_BAR; PG8_SCHED;
;             PG8_LDA(At, 0, 1); PG8_STAGE(PG8_SB(0, 0), b2, voffB); PG8_STAGE(PG8_SB(0, 1), b2 + hstep, voffB); PG8_STAGE(PG8_SA(0, 0), a2, voffA);
.LBB0_139:
	s_add_i32 s50, s46, 2
	s_add_u32 s47, s44, s0
	s_addc_u32 s51, s45, s1
	s_add_u32 s52, s47, 0x100
	s_addc_u32 s47, s51, 0
	s_add_u32 s51, s48, s0
	s_addc_u32 s53, s49, s1
	s_add_i32 s73, 0, 0x10000
	s_cmp_eq_u32 s67, s46
	s_cselect_b32 s47, s23, s47
	s_cselect_b32 s46, s22, s52
	v_add_u32_e32 v0, s73, v222
	s_cselect_b32 s53, s43, s53
	s_cselect_b32 s52, s42, s51
	s_add_i32 s51, 0, 0x14000
	ds_read_b128 v[130:133], v0
	ds_read_b128 v[134:137], v0 offset:1024
	ds_read_b128 v[138:141], v0 offset:2048
	ds_read_b128 v[142:145], v0 offset:3072
	v_add_u32_e32 v0, s51, v222
	ds_read_b128 v[146:149], v0
	ds_read_b128 v[150:153], v0 offset:1024
	ds_read_b128 v[154:157], v0 offset:2048
	ds_read_b128 v[158:161], v0 offset:3072
	s_sub_u32 vcc_lo, s0, s34
	s_subb_u32 vcc_hi, s1, 0
	s_mov_b32 m0, s65
	v_lshl_add_u64 v[234:235], v[208:209], 0, vcc
	v_lshl_add_u64 v[236:237], v[210:211], 0, vcc
	global_load_lds_dwordx4 v[234:235], off
	s_mov_b32 m0, s66
	s_nop 0
	global_load_lds_dwordx4 v[236:237], off
	v_lshl_add_u64 v[234:235], v[208:209], 0, s[0:1]
	s_add_i32 m0, s58, 0xc000
	ds_read_b128 v[162:165], v231
	ds_read_b128 v[166:169], v231 offset:1024
	ds_read_b128 v[170:173], v231 offset:2048
	ds_read_b128 v[174:177], v231 offset:3072
	ds_read_b128 v[178:181], v231 offset:4096
	ds_read_b128 v[182:185], v231 offset:5120
	ds_read_b128 v[186:189], v231 offset:6144
	ds_read_b128 v[190:193], v231 offset:7168
	global_load_lds_dwordx4 v[234:235], off
	v_lshl_add_u64 v[234:235], v[210:211], 0, s[0:1]
	s_add_i32 m0, s58, 0xe000
	s_nop 0
	global_load_lds_dwordx4 v[234:235], off
	s_waitcnt vmcnt(8)
	s_waitcnt lgkmcnt(0)
	s_barrier
	s_waitcnt lgkmcnt(0)
	v_mfma_f32_16x16x32_bf16 v[126:129], v[130:133], v[162:165], v[126:129]
	v_mfma_f32_16x16x32_bf16 v[122:125], v[138:141], v[162:165], v[122:125]
	v_mfma_f32_16x16x32_bf16 v[110:113], v[130:133], v[170:173], v[110:113]
	v_mfma_f32_16x16x32_bf16 v[106:109], v[138:141], v[170:173], v[106:109]
	v_mfma_f32_16x16x32_bf16 v[94:97], v[130:133], v[178:181], v[94:97]
	v_mfma_f32_16x16x32_bf16 v[90:93], v[138:141], v[178:181], v[90:93]
	v_mfma_f32_16x16x32_bf16 v[78:81], v[130:133], v[186:189], v[78:81]
	v_mfma_f32_16x16x32_bf16 v[74:77], v[138:141], v[186:189], v[74:77]
	v_mfma_f32_16x16x32_bf16 v[126:129], v[134:137], v[166:169], v[126:129]
	v_mfma_f32_16x16x32_bf16 v[122:125], v[142:145], v[166:169], v[122:125]
	v_mfma_f32_16x16x32_bf16 v[110:113], v[134:137], v[174:177], v[110:113]
	v_mfma_f32_16x16x32_bf16 v[106:109], v[142:145], v[174:177], v[106:109]
	v_mfma_f32_16x16x32_bf16 v[94:97], v[134:137], v[182:185], v[94:97]
	v_mfma_f32_16x16x32_bf16 v[90:93], v[142:145], v[182:185], v[90:93]
	v_mfma_f32_16x16x32_bf16 v[78:81], v[134:137], v[190:193], v[78:81]
	v_mfma_f32_16x16x32_bf16 v[74:77], v[142:145], v[190:193], v[74:77]
	v_mfma_f32_16x16x32_bf16 v[118:121], v[146:149], v[162:165], v[118:121]
	v_mfma_f32_16x16x32_bf16 v[114:117], v[154:157], v[162:165], v[114:117]
	v_mfma_f32_16x16x32_bf16 v[102:105], v[146:149], v[170:173], v[102:105]
	v_mfma_f32_16x16x32_bf16 v[98:101], v[154:157], v[170:173], v[98:101]
	v_mfma_f32_16x16x32_bf16 v[86:89], v[146:149], v[178:181], v[86:89]
	v_mfma_f32_16x16x32_bf16 v[82:85], v[154:157], v[178:181], v[82:85]
	v_mfma_f32_16x16x32_bf16 v[70:73], v[146:149], v[186:189], v[70:73]
	v_mfma_f32_16x16x32_bf16 v[66:69], v[154:157], v[186:189], v[66:69]
	v_mfma_f32_16x16x32_bf16 v[118:121], v[150:153], v[166:169], v[118:121]
	v_mfma_f32_16x16x32_bf16 v[114:117], v[158:161], v[166:169], v[114:117]
	v_mfma_f32_16x16x32_bf16 v[102:105], v[150:153], v[174:177], v[102:105]
	v_mfma_f32_16x16x32_bf16 v[98:101], v[158:161], v[174:177], v[98:101]
	v_mfma_f32_16x16x32_bf16 v[86:89], v[150:153], v[182:185], v[86:89]
	v_mfma_f32_16x16x32_bf16 v[82:85], v[158:161], v[182:185], v[82:85]
	v_mfma_f32_16x16x32_bf16 v[70:73], v[150:153], v[190:193], v[70:73]
	v_mfma_f32_16x16x32_bf16 v[66:69], v[158:161], v[190:193], v[66:69]
	s_barrier
	s_add_i32 s73, s73, s57
	v_lshl_add_u64 v[234:235], s[52:53], 0, v[198:199]
	s_mov_b32 m0, s73
	ds_read_b128 v[162:165], v231 offset:16384
	ds_read_b128 v[166:169], v231 offset:17408
	ds_read_b128 v[170:173], v231 offset:18432
	ds_read_b128 v[174:177], v231 offset:19456
	ds_read_b128 v[178:181], v231 offset:20480
	ds_read_b128 v[182:185], v231 offset:21504
	ds_read_b128 v[186:189], v231 offset:22528
	ds_read_b128 v[190:193], v231 offset:23552
	global_load_lds_dwordx4 v[234:235], off
	s_add_i32 m0, s73, 0x2000
	v_lshl_add_u64 v[236:237], s[52:53], 0, v[202:203]
	s_add_u32 s52, s52, s34
	s_addc_u32 s53, s53, 0
	s_add_i32 s51, s51, s57
	global_load_lds_dwordx4 v[236:237], off
	v_lshl_add_u64 v[238:239], s[52:53], 0, v[198:199]
	s_mov_b32 m0, s51
	v_lshl_add_u64 v[240:241], s[52:53], 0, v[202:203]
	global_load_lds_dwordx4 v[238:239], off
	s_add_i32 m0, s51, 0x2000
	v_lshl_add_u64 v[242:243], s[46:47], 0, v[196:197]
	global_load_lds_dwordx4 v[240:241], off
	v_lshl_add_u64 v[244:245], s[46:47], 0, v[200:201]
	s_waitcnt vmcnt(6)
	s_waitcnt lgkmcnt(0)
	s_barrier
; #define PG8_STAGE(bufoff, gbase, voff) do { _Pragma("unroll") for (int _i = 0; _i < 2; ++_i) \
;         __builtin_amdgcn_global_load_lds((const unsigned*)((const char*)(gbase) + (voff)[_i]), (PG8_LAS unsigned*)(lds + (bufoff) + ldsw + _i * 8192), 16, 0, 0); } while (0)
; #define PG8_LDA(dst, b, h) do { _Pragma("unroll") for (int m = 0; m < 4; ++m) _Pragma("unroll") for (int k = 0; k < 2; ++k) dst[m][k] = *(const PG8_LAS bf16x8*)(lds + PG8_SA(b, h) + aoff + m * 2048 + k * 1024); } while (0)
; #define PG8_LDB(dst, b, h) do { _Pragma("unroll") for (int n = 0; n < 2; ++n) _Pragma("unroll") for (int k = 0; k < 2; ++k) dst[n][k] = *(const PG8_LAS bf16x8*)(lds + PG8_SB(b, h) + boff + n * 2048 + k * 1024); } while (0)
; #define PG8_MMA(ai, bj, At, Bt) do { __builtin_amdgcn_s_setprio(1); _Pragma("unroll") for (int m = 0; m < 4; ++m) _Pragma("unroll") for (int n = 0; n < 2; ++n) _Pragma("unroll") for (int k = 0; k < 2; ++k) \
;         acc[ai][bj][m][n] = __builtin_amdgcn_mfma_f32_16x16x32_bf16(Bt[n][k], At[m][k], acc[ai][bj][m][n], 0, 0, 0); __builtin_amdgcn_s_setprio(0); } while (0)
; #define PG8_WAIT_V(n) asm volatile("s_waitcnt vmcnt(" #n ")" ::: "memory")
; #define PG8_WAIT_L(n) asm volatile("s_waitcnt lgkmcnt(" #n ")" ::: "memory")
; #define PG8_BAR __builtin_amdgcn_s_barrier()
; #define PG8_SCHED __builtin_amdgcn_sched_barrier(0)
; template <class Epi, class Sched, bool ALIGN_EPI = false, bool SP2 = false>
; __device__ __forceinline__ void gemm_phase(PG8_LAS unsigned char* lds, const Gemm g, const Sched& S, const Epi& E, const int tid_in) {
;     ...
;             PG8_WAIT_V(8); PG8_WAIT_L(0); PG8_BAR; PG8_MMA(1, 0, At, B0); PG8_MMA(1, 1, At, B1); PG8_BAR; PG8_SCHED;
;             PG8_LDB(B0, 1, 0); PG8_LDB(B1, 1, 1); PG8_SCHED; PG8_LDA(At, 1, 0); PG8_STAGE(PG8_SA(0, 1), a2 + hstep, voffA);
	s_waitcnt lgkmcnt(0)
	v_mfma_f32_16x16x32_bf16 v[62:65], v[130:133], v[162:165], v[62:65]
	v_mfma_f32_16x16x32_bf16 v[58:61], v[138:141], v[162:165], v[58:61]
	v_mfma_f32_16x16x32_bf16 v[46:49], v[130:133], v[170:173], v[46:49]
	v_mfma_f32_16x16x32_bf16 v[42:45], v[138:141], v[170:173], v[42:45]
	v_mfma_f32_16x16x32_bf16 v[30:33], v[130:133], v[178:181], v[30:33]
	v_mfma_f32_16x16x32_bf16 v[26:29], v[138:141], v[178:181], v[26:29]
	v_mfma_f32_16x16x32_bf16 v[14:17], v[130:133], v[186:189], v[14:17]
	v_mfma_f32_16x16x32_bf16 v[10:13], v[138:141], v[186:189], v[10:13]
	v_mfma_f32_16x16x32_bf16 v[62:65], v[134:137], v[166:169], v[62:65]
	v_mfma_f32_16x16x32_bf16 v[58:61], v[142:145], v[166:169], v[58:61]
	v_mfma_f32_16x16x32_bf16 v[46:49], v[134:137], v[174:177], v[46:49]
	v_mfma_f32_16x16x32_bf16 v[42:45], v[142:145], v[174:177], v[42:45]
	v_mfma_f32_16x16x32_bf16 v[30:33], v[134:137], v[182:185], v[30:33]
	v_mfma_f32_16x16x32_bf16 v[26:29], v[142:145], v[182:185], v[26:29]
	v_mfma_f32_16x16x32_bf16 v[14:17], v[134:137], v[190:193], v[14:17]
	v_mfma_f32_16x16x32_bf16 v[10:13], v[142:145], v[190:193], v[10:13]
	v_mfma_f32_16x16x32_bf16 v[54:57], v[146:149], v[162:165], v[54:57]
	v_mfma_f32_16x16x32_bf16 v[50:53], v[154:157], v[162:165], v[50:53]
	v_mfma_f32_16x16x32_bf16 v[38:41], v[146:149], v[170:173], v[38:41]
	v_mfma_f32_16x16x32_bf16 v[34:37], v[154:157], v[170:173], v[34:37]
	v_mfma_f32_16x16x32_bf16 v[22:25], v[146:149], v[178:181], v[22:25]
	v_mfma_f32_16x16x32_bf16 v[18:21], v[154:157], v[178:181], v[18:21]
	v_mfma_f32_16x16x32_bf16 v[6:9], v[146:149], v[186:189], v[6:9]
	v_mfma_f32_16x16x32_bf16 v[2:5], v[154:157], v[186:189], v[2:5]
	v_mfma_f32_16x16x32_bf16 v[54:57], v[150:153], v[166:169], v[54:57]
	v_mfma_f32_16x16x32_bf16 v[50:53], v[158:161], v[166:169], v[50:53]
	v_mfma_f32_16x16x32_bf16 v[38:41], v[150:153], v[174:177], v[38:41]
	v_mfma_f32_16x16x32_bf16 v[34:37], v[158:161], v[174:177], v[34:37]
	v_mfma_f32_16x16x32_bf16 v[22:25], v[150:153], v[182:185], v[22:25]
	v_mfma_f32_16x16x32_bf16 v[18:21], v[158:161], v[182:185], v[18:21]
	v_mfma_f32_16x16x32_bf16 v[6:9], v[150:153], v[190:193], v[6:9]
	v_mfma_f32_16x16x32_bf16 v[2:5], v[158:161], v[190:193], v[2:5]
	s_barrier
	s_add_i32 s51, 0, 0x18000
	v_add_u32_e32 v0, s51, v222
	s_add_i32 s52, 0, 0x1c000
	ds_read_b128 v[130:133], v0
	ds_read_b128 v[134:137], v0 offset:1024
	ds_read_b128 v[138:141], v0 offset:2048
	ds_read_b128 v[142:145], v0 offset:3072
	v_add_u32_e32 v0, s52, v222
	ds_read_b128 v[146:149], v0
	ds_read_b128 v[150:153], v0 offset:1024
	ds_read_b128 v[154:157], v0 offset:2048
	ds_read_b128 v[158:161], v0 offset:3072
	s_mov_b32 m0, s58
	s_add_u32 s46, s46, s34
	global_load_lds_dwordx4 v[242:243], off
	s_mov_b32 m0, s59
	s_addc_u32 s47, s47, 0
	global_load_lds_dwordx4 v[244:245], off
	s_mov_b32 m0, s60
	v_lshl_add_u64 v[246:247], s[46:47], 0, v[196:197]
	ds_read_b128 v[162:165], v231 offset:32768
	ds_read_b128 v[166:169], v231 offset:33792
	ds_read_b128 v[170:173], v231 offset:34816
	ds_read_b128 v[174:177], v231 offset:35840
	ds_read_b128 v[178:181], v231 offset:36864
	ds_read_b128 v[182:185], v231 offset:37888
	ds_read_b128 v[186:189], v231 offset:38912
	ds_read_b128 v[190:193], v231 offset:39936
	global_load_lds_dwordx4 v[246:247], off
	v_lshl_add_u64 v[246:247], s[46:47], 0, v[200:201]
	s_mov_b32 m0, s61
	s_nop 0
	global_load_lds_dwordx4 v[246:247], off
	s_waitcnt vmcnt(8)
	s_waitcnt lgkmcnt(0)
	s_barrier
; #define PG8_STAGE(bufoff, gbase, voff) do { _Pragma("unroll") for (int _i = 0; _i < 2; ++_i) \
;         __builtin_amdgcn_global_load_lds((const unsigned*)((const char*)(gbase) + (voff)[_i]), (PG8_LAS unsigned*)(lds + (bufoff) + ldsw + _i * 8192), 16, 0, 0); } while (0)
; #define PG8_LDA(dst, b, h) do { _Pragma("unroll") for (int m = 0; m < 4; ++m) _Pragma("unroll") for (int k = 0; k < 2; ++k) dst[m][k] = *(const PG8_LAS bf16x8*)(lds + PG8_SA(b, h) + aoff + m * 2048 + k * 1024); } while (0)
; #define PG8_MMA(ai, bj, At, Bt) do { __builtin_amdgcn_s_setprio(1); _Pragma("unroll") for (int m = 0; m < 4; ++m) _Pragma("unroll") for (int n = 0; n < 2; ++n) _Pragma("unroll") for (int k = 0; k < 2; ++k) \
;         acc[ai][bj][m][n] = __builtin_amdgcn_mfma_f32_16x16x32_bf16(Bt[n][k], At[m][k], acc[ai][bj][m][n], 0, 0, 0); __builtin_amdgcn_s_setprio(0); } while (0)
; #define PG8_WAIT_V(n) asm volatile("s_waitcnt vmcnt(" #n ")" ::: "memory")
; #define PG8_WAIT_L(n) asm volatile("s_waitcnt lgkmcnt(" #n ")" ::: "memory")
; #define PG8_BAR __builtin_amdgcn_s_barrier()
; #define PG8_SCHED __builtin_amdgcn_sched_barrier(0)
; template <class Epi, class Sched, bool ALIGN_EPI = false, bool SP2 = false>
; __device__ __forceinline__ void gemm_phase(PG8_LAS unsigned char* lds, const Gemm g, const Sched& S, const Epi& E, const int tid_in) {
;     ...
;             PG8_WAIT_V(8); PG8_WAIT_L(0); PG8_BAR; PG8_MMA(0, 0, At, B0); PG8_MMA(0, 1, At, B1); PG8_BAR; PG8_SCHED;
;             PG8_LDA(At, 1, 1); PG8_STAGE(PG8_SB(1, 0), b3, voffB); PG8_STAGE(PG8_SB(1, 1), b3 + hstep, voffB); PG8_STAGE(PG8_SA(1, 0), a3, voffA);
;             PG8_WAIT_V(8); PG8_WAIT_L(0); PG8_BAR; PG8_MMA(1, 0, At, B0); PG8_MMA(1, 1, At, B1); PG8_BAR; PG8_SCHED;
	s_waitcnt lgkmcnt(0)
	v_mfma_f32_16x16x32_bf16 v[126:129], v[130:133], v[162:165], v[126:129]
	v_mfma_f32_16x16x32_bf16 v[122:125], v[138:141], v[162:165], v[122:125]
	v_mfma_f32_16x16x32_bf16 v[110:113], v[130:133], v[170:173], v[110:113]
	v_mfma_f32_16x16x32_bf16 v[106:109], v[138:141], v[170:173], v[106:109]
	v_mfma_f32_16x16x32_bf16 v[94:97], v[130:133], v[178:181], v[94:97]
	v_mfma_f32_16x16x32_bf16 v[90:93], v[138:141], v[178:181], v[90:93]
	v_mfma_f32_16x16x32_bf16 v[78:81], v[130:133], v[186:189], v[78:81]
	v_mfma_f32_16x16x32_bf16 v[74:77], v[138:141], v[186:189], v[74:77]
	v_mfma_f32_16x16x32_bf16 v[126:129], v[134:137], v[166:169], v[126:129]
	v_mfma_f32_16x16x32_bf16 v[122:125], v[142:145], v[166:169], v[122:125]
	v_mfma_f32_16x16x32_bf16 v[110:113], v[134:137], v[174:177], v[110:113]
	v_mfma_f32_16x16x32_bf16 v[106:109], v[142:145], v[174:177], v[106:109]
	v_mfma_f32_16x16x32_bf16 v[94:97], v[134:137], v[182:185], v[94:97]
	v_mfma_f32_16x16x32_bf16 v[90:93], v[142:145], v[182:185], v[90:93]
	v_mfma_f32_16x16x32_bf16 v[78:81], v[134:137], v[190:193], v[78:81]
	v_mfma_f32_16x16x32_bf16 v[74:77], v[142:145], v[190:193], v[74:77]
	v_mfma_f32_16x16x32_bf16 v[118:121], v[146:149], v[162:165], v[118:121]
	v_mfma_f32_16x16x32_bf16 v[114:117], v[154:157], v[162:165], v[114:117]
	v_mfma_f32_16x16x32_bf16 v[102:105], v[146:149], v[170:173], v[102:105]
	v_mfma_f32_16x16x32_bf16 v[98:101], v[154:157], v[170:173], v[98:101]
	v_mfma_f32_16x16x32_bf16 v[86:89], v[146:149], v[178:181], v[86:89]
	v_mfma_f32_16x16x32_bf16 v[82:85], v[154:157], v[178:181], v[82:85]
	v_mfma_f32_16x16x32_bf16 v[70:73], v[146:149], v[186:189], v[70:73]
	v_mfma_f32_16x16x32_bf16 v[66:69], v[154:157], v[186:189], v[66:69]
	v_mfma_f32_16x16x32_bf16 v[118:121], v[150:153], v[166:169], v[118:121]
	v_mfma_f32_16x16x32_bf16 v[114:117], v[158:161], v[166:169], v[114:117]
	v_mfma_f32_16x16x32_bf16 v[102:105], v[150:153], v[174:177], v[102:105]
	v_mfma_f32_16x16x32_bf16 v[98:101], v[158:161], v[174:177], v[98:101]
	v_mfma_f32_16x16x32_bf16 v[86:89], v[150:153], v[182:185], v[86:89]
	v_mfma_f32_16x16x32_bf16 v[82:85], v[158:161], v[182:185], v[82:85]
	v_mfma_f32_16x16x32_bf16 v[70:73], v[150:153], v[190:193], v[70:73]
	v_mfma_f32_16x16x32_bf16 v[66:69], v[158:161], v[190:193], v[66:69]
	s_barrier
	s_add_i32 s46, s51, s57
	v_lshl_add_u64 v[234:235], v[234:235], 0, s[36:37]
	s_mov_b32 m0, s46
	ds_read_b128 v[162:165], v231 offset:49152
	ds_read_b128 v[166:169], v231 offset:50176
	ds_read_b128 v[170:173], v231 offset:51200
	ds_read_b128 v[174:177], v231 offset:52224
	ds_read_b128 v[178:181], v231 offset:53248
	ds_read_b128 v[182:185], v231 offset:54272
	ds_read_b128 v[186:189], v231 offset:55296
	ds_read_b128 v[190:193], v231 offset:56320
	global_load_lds_dwordx4 v[234:235], off
	v_lshl_add_u64 v[234:235], v[236:237], 0, s[36:37]
	s_add_i32 m0, s46, 0x2000
	s_add_i32 s46, s52, s57
	global_load_lds_dwordx4 v[234:235], off
	v_lshl_add_u64 v[234:235], v[238:239], 0, s[36:37]
	s_mov_b32 m0, s46
	s_nop 0
	global_load_lds_dwordx4 v[234:235], off
	v_lshl_add_u64 v[234:235], v[240:241], 0, s[36:37]
	s_add_i32 m0, s46, 0x2000
	s_nop 0
	global_load_lds_dwordx4 v[234:235], off
	s_waitcnt vmcnt(6)
	s_waitcnt lgkmcnt(0)
	s_barrier
	s_waitcnt lgkmcnt(0)
	v_mfma_f32_16x16x32_bf16 v[62:65], v[130:133], v[162:165], v[62:65]
	v_mfma_f32_16x16x32_bf16 v[58:61], v[138:141], v[162:165], v[58:61]
	v_mfma_f32_16x16x32_bf16 v[46:49], v[130:133], v[170:173], v[46:49]
	v_mfma_f32_16x16x32_bf16 v[42:45], v[138:141], v[170:173], v[42:45]
	v_mfma_f32_16x16x32_bf16 v[30:33], v[130:133], v[178:181], v[30:33]
	v_mfma_f32_16x16x32_bf16 v[26:29], v[138:141], v[178:181], v[26:29]
	v_mfma_f32_16x16x32_bf16 v[14:17], v[130:133], v[186:189], v[14:17]
	v_mfma_f32_16x16x32_bf16 v[10:13], v[138:141], v[186:189], v[10:13]
	v_mfma_f32_16x16x32_bf16 v[62:65], v[134:137], v[166:169], v[62:65]
	v_mfma_f32_16x16x32_bf16 v[58:61], v[142:145], v[166:169], v[58:61]
	v_mfma_f32_16x16x32_bf16 v[46:49], v[134:137], v[174:177], v[46:49]
	v_mfma_f32_16x16x32_bf16 v[42:45], v[142:145], v[174:177], v[42:45]
	v_mfma_f32_16x16x32_bf16 v[30:33], v[134:137], v[182:185], v[30:33]
	v_mfma_f32_16x16x32_bf16 v[26:29], v[142:145], v[182:185], v[26:29]
	v_mfma_f32_16x16x32_bf16 v[14:17], v[134:137], v[190:193], v[14:17]
	v_mfma_f32_16x16x32_bf16 v[10:13], v[142:145], v[190:193], v[10:13]
	v_mfma_f32_16x16x32_bf16 v[54:57], v[146:149], v[162:165], v[54:57]
	v_mfma_f32_16x16x32_bf16 v[50:53], v[154:157], v[162:165], v[50:53]
	v_mfma_f32_16x16x32_bf16 v[38:41], v[146:149], v[170:173], v[38:41]
	v_mfma_f32_16x16x32_bf16 v[34:37], v[154:157], v[170:173], v[34:37]
	v_mfma_f32_16x16x32_bf16 v[22:25], v[146:149], v[178:181], v[22:25]
	v_mfma_f32_16x16x32_bf16 v[18:21], v[154:157], v[178:181], v[18:21]
	v_mfma_f32_16x16x32_bf16 v[6:9], v[146:149], v[186:189], v[6:9]
	v_mfma_f32_16x16x32_bf16 v[2:5], v[154:157], v[186:189], v[2:5]
	v_mfma_f32_16x16x32_bf16 v[54:57], v[150:153], v[166:169], v[54:57]
	v_mfma_f32_16x16x32_bf16 v[50:53], v[158:161], v[166:169], v[50:53]
	v_mfma_f32_16x16x32_bf16 v[38:41], v[150:153], v[174:177], v[38:41]
	v_mfma_f32_16x16x32_bf16 v[34:37], v[158:161], v[174:177], v[34:37]
	v_mfma_f32_16x16x32_bf16 v[22:25], v[150:153], v[182:185], v[22:25]
	v_mfma_f32_16x16x32_bf16 v[18:21], v[158:161], v[182:185], v[18:21]
	v_mfma_f32_16x16x32_bf16 v[6:9], v[150:153], v[190:193], v[6:9]
	v_mfma_f32_16x16x32_bf16 v[2:5], v[158:161], v[190:193], v[2:5]
	s_barrier
	s_add_u32 s0, s0, 0x100
	s_addc_u32 s1, s1, 0
	s_cmp_ge_u32 s50, s63
	s_mov_b32 s46, s50
	s_cbranch_scc1 .LBB0_142
